# window interior tiles skip the band mask (unmasked tile body)
# speedup vs baseline: 1.0018x; 1.0009x over previous
; #define ATT_LAS __attribute__((address_space(3)))
; __device__ __forceinline__ int crow(int r, int hi) { return (r & 3) + 8 * (r >> 2) + 4 * hi; }
; __device__ __forceinline__ void attn_unit(int uv, const float* sink_l, const bf16_t* P, bf16_t* Y, ATT_LAS unsigned char* lds, const float* rpb_l, const float* qn_l, const float* kn_l) {
;     ...
;                 const ATT_LAS unsigned char* Kb = ATT_KBUF(cur); const ATT_LAS unsigned char* Vb = ATT_VBUF(cur);
;                 f32x16 p0 = {}, p1 = {};
; #pragma unroll
;                 for (int d0 = 0; d0 < 4; ++d0) {
;                     const bf16x8 k0 = *(const ATT_LAS bf16x8*)(Kb + kfrag + d0 * 2048);
;                     const bf16x8 k1 = *(const ATT_LAS bf16x8*)(Kb + kfrag + d0 * 2048 + 512);
;                     p0 = __builtin_amdgcn_mfma_f32_32x32x16_bf16(k0, qf[d0], p0, 0, 0, 0);
;                     p1 = __builtin_amdgcn_mfma_f32_32x32x16_bf16(k1, qf[d0], p1, 0, 0, 0);
;                 }
;                 if (a.mode == 1) { const int dq = tl * 64 - (qw + r32);
; #pragma unroll
;                     for (int r = 0; r < 16; ++r) { const int d = dq + crow(r, hi); if (d > 128 || d < -128) p0[r] = NEGF; if (d + 32 > 128 || d + 32 < -128) p1[r] = NEGF; } }
;                 else { const int qc = 32 * (wid & 1) + r32, cs = clampi(qc - 8, 0, 48); const ATT_LAS float* trow = tbl + (tl - qr + 7) * 31 + 15 - qc;
; #pragma unroll
;                     for (int r = 0; r < 16; ++r) { const int kcl = crow(r, hi);
;                         const float b0 = trow[kcl], b1 = trow[kcl + 32];
;                         p0[r] = ((unsigned)(kcl - cs) < 16u) ? p0[r] + b0 : NEGF;
;                         p1[r] = ((unsigned)(kcl + 32 - cs) < 16u) ? p1[r] + b1 : NEGF; } }
;                 const float mt = rowmax32(p0, p1);
;                 if (__any(mt > m)) { const float mn = fmaxf(m, mt), alpha = __builtin_amdgcn_exp2f(m - mn); m = mn; lsum *= alpha;
; #pragma unroll
;                     for (int r = 0; r < 16; ++r) { o0[r] *= alpha; o1[r] *= alpha; } }
.Lmk_ctx_body:
	ds_read_b64_tr_b16 v[160:161], v242 offset:24576
	ds_read_b64_tr_b16 v[162:163], v242 offset:25088
	ds_read_b64_tr_b16 v[176:177], v242 offset:28672
	ds_read_b64_tr_b16 v[178:179], v242 offset:29184
	ds_read_b64_tr_b16 v[164:165], v242 offset:25600
	ds_read_b64_tr_b16 v[166:167], v242 offset:26112
	ds_read_b64_tr_b16 v[180:181], v242 offset:29696
	s_waitcnt lgkmcnt(14)
	v_mfma_f32_32x32x16_bf16 v[80:95], v[128:131], v[96:99], 0
	ds_read_b64_tr_b16 v[182:183], v242 offset:30208
	s_waitcnt lgkmcnt(14)
	v_mfma_f32_32x32x16_bf16 v[48:63], v[132:135], v[96:99], 0
	ds_read_b64_tr_b16 v[168:169], v242 offset:26624
	s_waitcnt lgkmcnt(14)
	v_mfma_f32_32x32x16_bf16 v[80:95], v[136:139], v[100:103], v[80:95]
	ds_read_b64_tr_b16 v[170:171], v242 offset:27136
	s_waitcnt lgkmcnt(14)
	v_mfma_f32_32x32x16_bf16 v[48:63], v[140:143], v[100:103], v[48:63]
	ds_read_b64_tr_b16 v[184:185], v242 offset:30720
	s_waitcnt lgkmcnt(14)
	v_mfma_f32_32x32x16_bf16 v[80:95], v[144:147], v[104:107], v[80:95]
	ds_read_b64_tr_b16 v[186:187], v242 offset:31232
	s_waitcnt lgkmcnt(14)
	v_mfma_f32_32x32x16_bf16 v[48:63], v[148:151], v[104:107], v[48:63]
	ds_read_b64_tr_b16 v[172:173], v242 offset:27648
	s_waitcnt lgkmcnt(14)
	v_mfma_f32_32x32x16_bf16 v[80:95], v[152:155], v[108:111], v[80:95]
	ds_read_b64_tr_b16 v[174:175], v242 offset:28160
	s_waitcnt lgkmcnt(14)
	v_mfma_f32_32x32x16_bf16 v[48:63], v[156:159], v[108:111], v[48:63]
	ds_read_b64_tr_b16 v[188:189], v242 offset:31744
	s_waitcnt lgkmcnt(14)
	ds_read_b64_tr_b16 v[190:191], v242 offset:32256
	s_nop 7
	s_nop 0
	v_max3_f32 v204, v80, v81, v82
	v_max3_f32 v205, v83, v84, v85
	v_max3_f32 v204, v204, v86, v87
	v_max3_f32 v205, v205, v88, v89
	v_max3_f32 v204, v204, v90, v91
	v_max3_f32 v205, v205, v92, v93
	v_max3_f32 v204, v204, v94, v95
	v_max3_f32 v205, v205, v48, v49
	v_max3_f32 v204, v204, v50, v51
	v_max3_f32 v205, v205, v52, v53
	v_max3_f32 v204, v204, v54, v55
	v_max3_f32 v205, v205, v56, v57
	v_max3_f32 v204, v204, v58, v59
	v_max3_f32 v205, v205, v60, v61
	v_max3_f32 v204, v204, v62, v63
	v_max_f32_e32 v204, v204, v205
	v_mov_b32_e32 v205, v204
	s_nop 1
	v_permlane32_swap_b32_e32 v204, v205
	v_max_f32_e32 v204, v204, v205
	v_cmp_gt_f32_e32 vcc, v204, v202
	s_cbranch_vccz .Lnb_ctx_norescale
	v_max_f32_e32 v205, v202, v204
	v_sub_f32_e32 v208, v202, v205
	v_exp_f32_e32 v208, v208
	v_mov_b32_e32 v202, v205
	v_pk_mul_f32 v[0:1], v[0:1], v[208:209] op_sel_hi:[1,0]
	v_pk_mul_f32 v[2:3], v[2:3], v[208:209] op_sel_hi:[1,0]
	v_pk_mul_f32 v[4:5], v[4:5], v[208:209] op_sel_hi:[1,0]
	v_pk_mul_f32 v[6:7], v[6:7], v[208:209] op_sel_hi:[1,0]
	v_pk_mul_f32 v[8:9], v[8:9], v[208:209] op_sel_hi:[1,0]
	v_pk_mul_f32 v[10:11], v[10:11], v[208:209] op_sel_hi:[1,0]
	v_pk_mul_f32 v[12:13], v[12:13], v[208:209] op_sel_hi:[1,0]
	v_pk_mul_f32 v[14:15], v[14:15], v[208:209] op_sel_hi:[1,0]
	v_pk_mul_f32 v[16:17], v[16:17], v[208:209] op_sel_hi:[1,0]
	v_pk_mul_f32 v[18:19], v[18:19], v[208:209] op_sel_hi:[1,0]
	v_pk_mul_f32 v[20:21], v[20:21], v[208:209] op_sel_hi:[1,0]
	v_pk_mul_f32 v[22:23], v[22:23], v[208:209] op_sel_hi:[1,0]
	v_pk_mul_f32 v[24:25], v[24:25], v[208:209] op_sel_hi:[1,0]
	v_pk_mul_f32 v[26:27], v[26:27], v[208:209] op_sel_hi:[1,0]
	v_pk_mul_f32 v[28:29], v[28:29], v[208:209] op_sel_hi:[1,0]
	v_pk_mul_f32 v[30:31], v[30:31], v[208:209] op_sel_hi:[1,0]
	v_mul_f32_e32 v124, v124, v208

; __device__ __forceinline__ void attn_unit(int uv, const float* sink_l, const bf16_t* P, bf16_t* Y, ATT_LAS unsigned char* lds, const float* rpb_l, const float* qn_l, const float* kn_l) {
;     ...
;             if (a.mode == 1) need = (tl * 64 + 63 >= qw - 128) && (tl * 64 <= qw + 31 + 128);
;             else { const int rs = clampi(qr - 4, 0, 120); need = (tl >= rs) && (tl < rs + 8); }
.Lmsk_win:
	s_add_i32 s72, s33, 31
	s_cmp_ge_i32 s92, s72
	s_cbranch_scc0 .Lmsk_win_edge
	s_add_i32 s72, s91, 0xffffffa2
	s_cmp_le_i32 s92, s72
	s_cbranch_scc1 .Lmk_ctx_body
